# W_out and W_down GEMM K-loops also rebalanced 4+4 LDS-DMA pieces per super-phase; all four main GEMM loops now use vmcnt 8/4/8/4
# speedup vs baseline: 1.0015x; 1.0015x over previous
;     __host__ __device__ bool next(int i, Unit& u) const { const int L = i * G + c; if (L >= nunits) return false; u.pm = pm; u.pn = L & 7; u.ko = (L >> 3) * klen; return true; }
; #define PG8_STAGE(bufoff, gbase, voff) do { _Pragma("unroll") for (int _i = 0; _i < 2; ++_i) \
;         __builtin_amdgcn_global_load_lds((const unsigned*)((const char*)(gbase) + (voff)[_i]), (PG8_LAS unsigned*)(lds + (bufoff) + ldsw + _i * 8192), 16, 0, 0); } while (0)
; #define PG8_LDA(dst, b, h) do { _Pragma("unroll") for (int m = 0; m < 4; ++m) _Pragma("unroll") for (int k = 0; k < 2; ++k) dst[m][k] = *(const PG8_LAS bf16x8*)(lds + PG8_SA(b, h) + aoff + m * 2048 + k * 1024); } while (0)
; #define PG8_LDB(dst, b, h) do { _Pragma("unroll") for (int n = 0; n < 2; ++n) _Pragma("unroll") for (int k = 0; k < 2; ++k) dst[n][k] = *(const PG8_LAS bf16x8*)(lds + PG8_SB(b, h) + boff + n * 2048 + k * 1024); } while (0)
; #define PG8_WAIT_V(n) asm volatile("s_waitcnt vmcnt(" #n ")" ::: "memory")
; template <class Epi, class Sched, bool ALIGN_EPI = false, bool SP2 = false>
; __device__ __forceinline__ void gemm_phase(PG8_LAS unsigned char* lds, const Gemm g, const Sched& S, const Epi& E) {
;     ...
;         const bool has_next = S.next(ui + 1, nxt);
;         const char* nA = has_next ? (const char*)g.A + (size_t)nxt.pm * tstep + (size_t)nxt.ko * 2 : cA; const char* nB = has_next ? (const char*)g.Bt + (size_t)nxt.pn * tstep + (size_t)nxt.ko * 2 : cB;
;         for (int t = 0; t < nt; t += 2) {
;             const bool last = (t == nt - 2);
;             const char* a1 = cA + (size_t)(t + 1) * kstep;
;             const char* a2 = last ? nA : cA + (size_t)(t + 2) * kstep; const char* b2 = last ? nB : cB + (size_t)(t + 2) * kstep;
;             const char* a3 = a2 + kstep; const char* b3 = b2 + kstep;
;             if (last && has_next) S.a_ready(nxt);
;             if constexpr (SP2) {
;             PG8_LDB(B0, 0, 0); PG8_LDB(B1, 0, 1); PG8_SCHED; PG8_LDA(At, 0, 0); PG8_STAGE(PG8_SA(1, 1), a1 + hstep, voffA);
;             PG8_WAIT_V(8); PG8_WAIT_L(0); PG8_BAR; PG8_MMA(0, 0, At, B0); PG8_MMA(0, 1, At, B1); PG8_BAR; PG8_SCHED;
;     ...
;         for (int a = 0; a < 2; ++a)
; #pragma unroll
;             for (int b = 0; b < 2; ++b)
; #pragma unroll
;                 for (int m = 0; m < 4; ++m)
; #pragma unroll
;                     for (int n = 0; n < 2; ++n) acc[a][b][m][n] = (f32x4){0.f, 0.f, 0.f, 0.f};
.LBB0_815:
	s_ashr_i32 s23, s22, 31
	s_lshl_b64 s[14:15], s[22:23], 20
	s_add_u32 s26, s12, s14
	s_addc_u32 s27, s13, s15
	s_and_b64 s[14:15], s[6:7], exec
	s_cselect_b32 s14, s27, s49
	s_cselect_b32 s15, s26, s48
	s_ashr_i32 s21, s20, 31
	s_lshl_b64 s[30:31], s[20:21], 20
	s_add_u32 s36, s67, s30
	s_addc_u32 s37, s70, s31
	s_and_b64 s[30:31], s[6:7], exec
	s_cselect_b32 s21, s37, s55
	s_cselect_b32 s23, s36, s54
	s_add_u32 s30, s54, 0x100
	v_mov_b32_e32 v0, 0
	s_addc_u32 s31, s55, 0
	s_mov_b32 s56, -2
	v_mov_b32_e32 v1, v0
	v_mov_b32_e32 v2, v0
	v_mov_b32_e32 v3, v0
	v_mov_b32_e32 v4, v0
	v_mov_b32_e32 v5, v0
	v_mov_b32_e32 v6, v0
	v_mov_b32_e32 v7, v0
	v_mov_b32_e32 v16, v0
	v_mov_b32_e32 v17, v0
	v_mov_b32_e32 v18, v0
	v_mov_b32_e32 v19, v0
	v_mov_b32_e32 v20, v0
	v_mov_b32_e32 v21, v0
	v_mov_b32_e32 v22, v0
	v_mov_b32_e32 v23, v0
	v_mov_b32_e32 v32, v0
	v_mov_b32_e32 v33, v0
	v_mov_b32_e32 v34, v0
	v_mov_b32_e32 v35, v0
	v_mov_b32_e32 v36, v0
	v_mov_b32_e32 v37, v0
	v_mov_b32_e32 v38, v0
	v_mov_b32_e32 v39, v0
	v_mov_b32_e32 v48, v0
	v_mov_b32_e32 v49, v0
	v_mov_b32_e32 v50, v0
	v_mov_b32_e32 v51, v0
	v_mov_b32_e32 v52, v0
	v_mov_b32_e32 v53, v0
	v_mov_b32_e32 v54, v0
	v_mov_b32_e32 v55, v0
	v_mov_b32_e32 v8, v0
	v_mov_b32_e32 v9, v0
	v_mov_b32_e32 v10, v0
	v_mov_b32_e32 v11, v0
	v_mov_b32_e32 v12, v0
	v_mov_b32_e32 v13, v0
	v_mov_b32_e32 v14, v0
	v_mov_b32_e32 v15, v0
	v_mov_b32_e32 v24, v0
	v_mov_b32_e32 v25, v0
	v_mov_b32_e32 v26, v0
	v_mov_b32_e32 v27, v0
	v_mov_b32_e32 v28, v0
	v_mov_b32_e32 v29, v0
	v_mov_b32_e32 v30, v0
	v_mov_b32_e32 v31, v0
	v_mov_b32_e32 v40, v0
	v_mov_b32_e32 v41, v0
	v_mov_b32_e32 v42, v0
	v_mov_b32_e32 v43, v0
	v_mov_b32_e32 v44, v0
	v_mov_b32_e32 v45, v0
	v_mov_b32_e32 v46, v0
	v_mov_b32_e32 v47, v0
	v_mov_b32_e32 v56, v0
	v_mov_b32_e32 v57, v0
	v_mov_b32_e32 v58, v0
	v_mov_b32_e32 v59, v0
	v_mov_b32_e32 v60, v0
	v_mov_b32_e32 v61, v0
	v_mov_b32_e32 v62, v0
	v_mov_b32_e32 v63, v0
	v_mov_b32_e32 v64, v0
	v_mov_b32_e32 v65, v0
	v_mov_b32_e32 v66, v0
	v_mov_b32_e32 v67, v0
	v_mov_b32_e32 v68, v0
	v_mov_b32_e32 v69, v0
	v_mov_b32_e32 v70, v0
	v_mov_b32_e32 v71, v0
	v_mov_b32_e32 v80, v0
	v_mov_b32_e32 v81, v0
	v_mov_b32_e32 v82, v0
	v_mov_b32_e32 v83, v0
	v_mov_b32_e32 v84, v0
	v_mov_b32_e32 v85, v0
	v_mov_b32_e32 v86, v0
	v_mov_b32_e32 v87, v0
	v_mov_b32_e32 v96, v0
	v_mov_b32_e32 v97, v0
	v_mov_b32_e32 v98, v0
	v_mov_b32_e32 v99, v0
	v_mov_b32_e32 v100, v0
	v_mov_b32_e32 v101, v0
	v_mov_b32_e32 v102, v0
	v_mov_b32_e32 v103, v0
	v_mov_b32_e32 v112, v0
	v_mov_b32_e32 v113, v0
	v_mov_b32_e32 v114, v0
	v_mov_b32_e32 v115, v0
	v_mov_b32_e32 v116, v0
	v_mov_b32_e32 v117, v0
	v_mov_b32_e32 v118, v0
	v_mov_b32_e32 v119, v0
	v_mov_b32_e32 v72, v0
	v_mov_b32_e32 v73, v0
	v_mov_b32_e32 v74, v0
	v_mov_b32_e32 v75, v0
	v_mov_b32_e32 v76, v0
	v_mov_b32_e32 v77, v0
	v_mov_b32_e32 v78, v0
	v_mov_b32_e32 v79, v0
	v_mov_b32_e32 v88, v0
	v_mov_b32_e32 v89, v0
	v_mov_b32_e32 v90, v0
	v_mov_b32_e32 v91, v0
	v_mov_b32_e32 v92, v0
	v_mov_b32_e32 v93, v0
	v_mov_b32_e32 v94, v0
	v_mov_b32_e32 v95, v0
	v_mov_b32_e32 v104, v0
	v_mov_b32_e32 v105, v0
	v_mov_b32_e32 v106, v0
	v_mov_b32_e32 v107, v0
	v_mov_b32_e32 v108, v0
	v_mov_b32_e32 v109, v0
	v_mov_b32_e32 v110, v0
	v_mov_b32_e32 v111, v0
	v_mov_b32_e32 v120, v0
	v_mov_b32_e32 v121, v0
	v_mov_b32_e32 v122, v0
	v_mov_b32_e32 v123, v0
	v_mov_b32_e32 v124, v0
	v_mov_b32_e32 v125, v0
	v_mov_b32_e32 v126, v0
	v_mov_b32_e32 v127, v0
	v_lshl_add_u64 v[224:225], s[48:49], 0, v[130:131]
	v_lshl_add_u64 v[226:227], s[48:49], 0, v[128:129]
.LBB0_816:
	s_add_u32 s54, s48, 0x100
	s_addc_u32 s55, s49, 0
	s_add_i32 s61, 0, 0x10000
	s_cmp_eq_u32 s56, 28
	s_cselect_b32 s65, s14, s55
	s_cselect_b32 s64, s15, s54
	v_add_u32_e32 v140, s61, v151
	s_cselect_b32 s63, s21, s31
	s_cselect_b32 s62, s23, s30
	s_add_i32 s78, 0, 0x14000
	ds_read_b128 v[136:139], v140
	ds_read_b128 v[146:149], v140 offset:1024
	ds_read_b128 v[154:157], v140 offset:2048
	ds_read_b128 v[160:163], v140 offset:3072
	v_add_u32_e32 v140, s78, v151
	ds_read_b128 v[164:167], v140
	ds_read_b128 v[168:171], v140 offset:1024
	ds_read_b128 v[172:175], v140 offset:2048
	ds_read_b128 v[176:179], v140 offset:3072
	v_lshl_add_u64 v[220:221], s[48:49], 0, v[132:133]
	s_add_i32 m0, s72, 0xc000
	ds_read_b128 v[180:183], v158
	ds_read_b128 v[184:187], v158 offset:1024
	ds_read_b128 v[188:191], v158 offset:2048
	ds_read_b128 v[192:195], v158 offset:3072
	ds_read_b128 v[196:199], v158 offset:4096
	ds_read_b128 v[208:211], v158 offset:5120
	ds_read_b128 v[212:215], v158 offset:6144
	ds_read_b128 v[216:219], v158 offset:7168
	global_load_lds_dwordx4 v[220:221], off
	v_lshl_add_u64 v[220:221], s[48:49], 0, v[134:135]
	s_add_i32 m0, s72, 0xe000
	s_nop 0
	global_load_lds_dwordx4 v[220:221], off
	v_lshl_add_u64 v[220:221], v[224:225], 0, s[84:85]
	s_mov_b32 m0, s91
	s_nop 0
	global_load_lds_dwordx4 v[220:221], off
	v_lshl_add_u64 v[220:221], v[226:227], 0, s[84:85]
	s_mov_b32 m0, s92
	s_nop 0
	global_load_lds_dwordx4 v[220:221], off
	s_waitcnt vmcnt(8)
	s_waitcnt lgkmcnt(0)
	s_barrier
; #define PG8_STAGE(bufoff, gbase, voff) do { _Pragma("unroll") for (int _i = 0; _i < 2; ++_i) \
;         __builtin_amdgcn_global_load_lds((const unsigned*)((const char*)(gbase) + (voff)[_i]), (PG8_LAS unsigned*)(lds + (bufoff) + ldsw + _i * 8192), 16, 0, 0); } while (0)
; #define PG8_LDA(dst, b, h) do { _Pragma("unroll") for (int m = 0; m < 4; ++m) _Pragma("unroll") for (int k = 0; k < 2; ++k) dst[m][k] = *(const PG8_LAS bf16x8*)(lds + PG8_SA(b, h) + aoff + m * 2048 + k * 1024); } while (0)
; #define PG8_LDB(dst, b, h) do { _Pragma("unroll") for (int n = 0; n < 2; ++n) _Pragma("unroll") for (int k = 0; k < 2; ++k) dst[n][k] = *(const PG8_LAS bf16x8*)(lds + PG8_SB(b, h) + boff + n * 2048 + k * 1024); } while (0)
; #define PG8_MMA(ai, bj, At, Bt) do { __builtin_amdgcn_s_setprio(1); _Pragma("unroll") for (int m = 0; m < 4; ++m) _Pragma("unroll") for (int n = 0; n < 2; ++n) _Pragma("unroll") for (int k = 0; k < 2; ++k) \
;         acc[ai][bj][m][n] = __builtin_amdgcn_mfma_f32_16x16x32_bf16(Bt[n][k], At[m][k], acc[ai][bj][m][n], 0, 0, 0); __builtin_amdgcn_s_setprio(0); } while (0)
; #define PG8_WAIT_V(n) asm volatile("s_waitcnt vmcnt(" #n ")" ::: "memory")
; #define PG8_WAIT_L(n) asm volatile("s_waitcnt lgkmcnt(" #n ")" ::: "memory")
; #define PG8_BAR __builtin_amdgcn_s_barrier()
; #define PG8_SCHED __builtin_amdgcn_sched_barrier(0)
; template <class Epi, class Sched, bool ALIGN_EPI = false, bool SP2 = false>
; __device__ __forceinline__ void gemm_phase(PG8_LAS unsigned char* lds, const Gemm g, const Sched& S, const Epi& E) {
;     ...
;             PG8_LDB(B0, 0, 0); PG8_LDB(B1, 0, 1); PG8_SCHED; PG8_LDA(At, 0, 0); PG8_STAGE(PG8_SA(1, 1), a1 + hstep, voffA);
;             PG8_WAIT_V(8); PG8_WAIT_L(0); PG8_BAR; PG8_MMA(0, 0, At, B0); PG8_MMA(0, 1, At, B1); PG8_BAR; PG8_SCHED;
;             PG8_LDA(At, 0, 1); PG8_STAGE(PG8_SB(0, 0), b2, voffB); PG8_STAGE(PG8_SB(0, 1), b2 + hstep, voffB); PG8_STAGE(PG8_SA(0, 0), a2, voffA);
;             PG8_WAIT_V(8); PG8_WAIT_L(0); PG8_BAR; PG8_MMA(1, 0, At, B0); PG8_MMA(1, 1, At, B1); PG8_BAR; PG8_SCHED;
	s_setprio 1
	s_waitcnt lgkmcnt(0)
	v_mfma_f32_16x16x32_bf16 v[124:127], v[136:139], v[180:183], v[124:127]
	v_mfma_f32_16x16x32_bf16 v[120:123], v[154:157], v[180:183], v[120:123]
	v_mfma_f32_16x16x32_bf16 v[108:111], v[136:139], v[188:191], v[108:111]
	v_mfma_f32_16x16x32_bf16 v[104:107], v[154:157], v[188:191], v[104:107]
	v_mfma_f32_16x16x32_bf16 v[92:95], v[136:139], v[196:199], v[92:95]
	v_mfma_f32_16x16x32_bf16 v[88:91], v[154:157], v[196:199], v[88:91]
	v_mfma_f32_16x16x32_bf16 v[76:79], v[136:139], v[212:215], v[76:79]
	v_mfma_f32_16x16x32_bf16 v[72:75], v[154:157], v[212:215], v[72:75]
	v_mfma_f32_16x16x32_bf16 v[124:127], v[146:149], v[184:187], v[124:127]
	v_mfma_f32_16x16x32_bf16 v[120:123], v[160:163], v[184:187], v[120:123]
	v_mfma_f32_16x16x32_bf16 v[108:111], v[146:149], v[192:195], v[108:111]
	v_mfma_f32_16x16x32_bf16 v[104:107], v[160:163], v[192:195], v[104:107]
	v_mfma_f32_16x16x32_bf16 v[92:95], v[146:149], v[208:211], v[92:95]
	v_mfma_f32_16x16x32_bf16 v[88:91], v[160:163], v[208:211], v[88:91]
	v_mfma_f32_16x16x32_bf16 v[76:79], v[146:149], v[216:219], v[76:79]
	v_mfma_f32_16x16x32_bf16 v[72:75], v[160:163], v[216:219], v[72:75]
	s_setprio 0
	s_setprio 1
	v_mfma_f32_16x16x32_bf16 v[116:119], v[164:167], v[180:183], v[116:119]
	v_mfma_f32_16x16x32_bf16 v[112:115], v[172:175], v[180:183], v[112:115]
	v_mfma_f32_16x16x32_bf16 v[100:103], v[164:167], v[188:191], v[100:103]
	v_mfma_f32_16x16x32_bf16 v[96:99], v[172:175], v[188:191], v[96:99]
	v_mfma_f32_16x16x32_bf16 v[84:87], v[164:167], v[196:199], v[84:87]
	v_mfma_f32_16x16x32_bf16 v[80:83], v[172:175], v[196:199], v[80:83]
	v_mfma_f32_16x16x32_bf16 v[68:71], v[164:167], v[212:215], v[68:71]
	v_mfma_f32_16x16x32_bf16 v[64:67], v[172:175], v[212:215], v[64:67]
	v_mfma_f32_16x16x32_bf16 v[116:119], v[168:171], v[184:187], v[116:119]
	v_mfma_f32_16x16x32_bf16 v[112:115], v[176:179], v[184:187], v[112:115]
	v_mfma_f32_16x16x32_bf16 v[100:103], v[168:171], v[192:195], v[100:103]
	v_mfma_f32_16x16x32_bf16 v[96:99], v[176:179], v[192:195], v[96:99]
	v_mfma_f32_16x16x32_bf16 v[84:87], v[168:171], v[208:211], v[84:87]
	v_mfma_f32_16x16x32_bf16 v[80:83], v[176:179], v[208:211], v[80:83]
	v_mfma_f32_16x16x32_bf16 v[68:71], v[168:171], v[216:219], v[68:71]
	v_mfma_f32_16x16x32_bf16 v[64:67], v[176:179], v[216:219], v[64:67]
	s_setprio 0
	s_barrier
	s_add_i32 s48, s61, s71
	v_lshl_add_u64 v[220:221], s[62:63], 0, v[130:131]
	s_mov_b32 m0, s48
	ds_read_b128 v[180:183], v158 offset:16384
	ds_read_b128 v[184:187], v158 offset:17408
	ds_read_b128 v[188:191], v158 offset:18432
	ds_read_b128 v[192:195], v158 offset:19456
	ds_read_b128 v[196:199], v158 offset:20480
	ds_read_b128 v[208:211], v158 offset:21504
	ds_read_b128 v[212:215], v158 offset:22528
	ds_read_b128 v[216:219], v158 offset:23552
	global_load_lds_dwordx4 v[220:221], off
	s_add_i32 m0, s48, 0x2000
	s_add_u32 s48, s62, 0x80000
	v_lshl_add_u64 v[222:223], s[62:63], 0, v[128:129]
	s_addc_u32 s49, s63, 0
	s_add_i32 s61, s78, s71
	global_load_lds_dwordx4 v[222:223], off
	v_lshl_add_u64 v[224:225], s[48:49], 0, v[130:131]
	s_mov_b32 m0, s61
	global_load_lds_dwordx4 v[224:225], off
	v_lshl_add_u64 v[224:225], s[48:49], 0, v[128:129]
	s_add_i32 m0, s61, 0x2000
	s_nop 0
	global_load_lds_dwordx4 v[224:225], off
	s_waitcnt vmcnt(4)
	s_waitcnt lgkmcnt(0)
	s_barrier
	s_setprio 1
	s_waitcnt lgkmcnt(0)
	v_mfma_f32_16x16x32_bf16 v[60:63], v[136:139], v[180:183], v[60:63]
	v_mfma_f32_16x16x32_bf16 v[56:59], v[154:157], v[180:183], v[56:59]
	v_mfma_f32_16x16x32_bf16 v[44:47], v[136:139], v[188:191], v[44:47]
	v_mfma_f32_16x16x32_bf16 v[40:43], v[154:157], v[188:191], v[40:43]
	v_mfma_f32_16x16x32_bf16 v[28:31], v[136:139], v[196:199], v[28:31]
	v_mfma_f32_16x16x32_bf16 v[24:27], v[154:157], v[196:199], v[24:27]
	v_mfma_f32_16x16x32_bf16 v[12:15], v[136:139], v[212:215], v[12:15]
	v_mfma_f32_16x16x32_bf16 v[8:11], v[154:157], v[212:215], v[8:11]
	v_mfma_f32_16x16x32_bf16 v[60:63], v[146:149], v[184:187], v[60:63]
	v_mfma_f32_16x16x32_bf16 v[56:59], v[160:163], v[184:187], v[56:59]
	v_mfma_f32_16x16x32_bf16 v[44:47], v[146:149], v[192:195], v[44:47]
	v_mfma_f32_16x16x32_bf16 v[40:43], v[160:163], v[192:195], v[40:43]
	v_mfma_f32_16x16x32_bf16 v[28:31], v[146:149], v[208:211], v[28:31]
	v_mfma_f32_16x16x32_bf16 v[24:27], v[160:163], v[208:211], v[24:27]
	v_mfma_f32_16x16x32_bf16 v[12:15], v[146:149], v[216:219], v[12:15]
	v_mfma_f32_16x16x32_bf16 v[8:11], v[160:163], v[216:219], v[8:11]
	s_setprio 0
	s_setprio 1
	v_mfma_f32_16x16x32_bf16 v[52:55], v[164:167], v[180:183], v[52:55]
	v_mfma_f32_16x16x32_bf16 v[48:51], v[172:175], v[180:183], v[48:51]
	v_mfma_f32_16x16x32_bf16 v[36:39], v[164:167], v[188:191], v[36:39]
	v_mfma_f32_16x16x32_bf16 v[32:35], v[172:175], v[188:191], v[32:35]
	v_mfma_f32_16x16x32_bf16 v[20:23], v[164:167], v[196:199], v[20:23]
	v_mfma_f32_16x16x32_bf16 v[16:19], v[172:175], v[196:199], v[16:19]
	v_mfma_f32_16x16x32_bf16 v[4:7], v[164:167], v[212:215], v[4:7]
	v_mfma_f32_16x16x32_bf16 v[0:3], v[172:175], v[212:215], v[0:3]
	v_mfma_f32_16x16x32_bf16 v[52:55], v[168:171], v[184:187], v[52:55]
	v_mfma_f32_16x16x32_bf16 v[48:51], v[176:179], v[184:187], v[48:51]
	v_mfma_f32_16x16x32_bf16 v[36:39], v[168:171], v[192:195], v[36:39]
	v_mfma_f32_16x16x32_bf16 v[32:35], v[176:179], v[192:195], v[32:35]
	v_mfma_f32_16x16x32_bf16 v[20:23], v[168:171], v[208:211], v[20:23]
	v_mfma_f32_16x16x32_bf16 v[16:19], v[176:179], v[208:211], v[16:19]
	v_mfma_f32_16x16x32_bf16 v[4:7], v[168:171], v[216:219], v[4:7]
	v_mfma_f32_16x16x32_bf16 v[0:3], v[176:179], v[216:219], v[0:3]
	s_setprio 0
	s_barrier
; #define PG8_STAGE(bufoff, gbase, voff) do { _Pragma("unroll") for (int _i = 0; _i < 2; ++_i) \
;         __builtin_amdgcn_global_load_lds((const unsigned*)((const char*)(gbase) + (voff)[_i]), (PG8_LAS unsigned*)(lds + (bufoff) + ldsw + _i * 8192), 16, 0, 0); } while (0)
; #define PG8_LDA(dst, b, h) do { _Pragma("unroll") for (int m = 0; m < 4; ++m) _Pragma("unroll") for (int k = 0; k < 2; ++k) dst[m][k] = *(const PG8_LAS bf16x8*)(lds + PG8_SA(b, h) + aoff + m * 2048 + k * 1024); } while (0)
; #define PG8_LDB(dst, b, h) do { _Pragma("unroll") for (int n = 0; n < 2; ++n) _Pragma("unroll") for (int k = 0; k < 2; ++k) dst[n][k] = *(const PG8_LAS bf16x8*)(lds + PG8_SB(b, h) + boff + n * 2048 + k * 1024); } while (0)
; #define PG8_MMA(ai, bj, At, Bt) do { __builtin_amdgcn_s_setprio(1); _Pragma("unroll") for (int m = 0; m < 4; ++m) _Pragma("unroll") for (int n = 0; n < 2; ++n) _Pragma("unroll") for (int k = 0; k < 2; ++k) \
;         acc[ai][bj][m][n] = __builtin_amdgcn_mfma_f32_16x16x32_bf16(Bt[n][k], At[m][k], acc[ai][bj][m][n], 0, 0, 0); __builtin_amdgcn_s_setprio(0); } while (0)
; #define PG8_WAIT_V(n) asm volatile("s_waitcnt vmcnt(" #n ")" ::: "memory")
; #define PG8_WAIT_L(n) asm volatile("s_waitcnt lgkmcnt(" #n ")" ::: "memory")
; #define PG8_BAR __builtin_amdgcn_s_barrier()
; #define PG8_SCHED __builtin_amdgcn_sched_barrier(0)
; template <class Epi, class Sched, bool ALIGN_EPI = false, bool SP2 = false>
; __device__ __forceinline__ void gemm_phase(PG8_LAS unsigned char* lds, const Gemm g, const Sched& S, const Epi& E) {
;     ...
;             PG8_LDB(B0, 1, 0); PG8_LDB(B1, 1, 1); PG8_SCHED; PG8_LDA(At, 1, 0); PG8_STAGE(PG8_SA(0, 1), a2 + hstep, voffA);
;             PG8_WAIT_V(8); PG8_WAIT_L(0); PG8_BAR; PG8_MMA(0, 0, At, B0); PG8_MMA(0, 1, At, B1); PG8_BAR; PG8_SCHED;
	s_add_i32 s61, 0, 0x18000
	v_add_u32_e32 v140, s61, v151
	s_add_i32 s78, 0, 0x1c000
	ds_read_b128 v[136:139], v140
	ds_read_b128 v[146:149], v140 offset:1024
	ds_read_b128 v[154:157], v140 offset:2048
	ds_read_b128 v[160:163], v140 offset:3072
	v_add_u32_e32 v140, s78, v151
	ds_read_b128 v[164:167], v140
	ds_read_b128 v[168:171], v140 offset:1024
	ds_read_b128 v[172:175], v140 offset:2048
	ds_read_b128 v[176:179], v140 offset:3072
	v_lshl_add_u64 v[224:225], s[64:65], 0, v[130:131]
	s_mov_b32 m0, s72
	s_nop 0
	global_load_lds_dwordx4 v[224:225], off
	v_lshl_add_u64 v[226:227], s[64:65], 0, v[128:129]
	s_mov_b32 m0, s73
	s_nop 0
	global_load_lds_dwordx4 v[226:227], off
	s_add_u32 s48, s64, 0x80000
	s_addc_u32 s49, s65, 0
	s_mov_b32 m0, s76
	v_lshl_add_u64 v[228:229], s[48:49], 0, v[130:131]
	ds_read_b128 v[180:183], v158 offset:32768
	ds_read_b128 v[184:187], v158 offset:33792
	ds_read_b128 v[188:191], v158 offset:34816
	ds_read_b128 v[192:195], v158 offset:35840
	ds_read_b128 v[196:199], v158 offset:36864
	ds_read_b128 v[208:211], v158 offset:37888
	ds_read_b128 v[212:215], v158 offset:38912
	ds_read_b128 v[216:219], v158 offset:39936
	global_load_lds_dwordx4 v[228:229], off
	v_lshl_add_u64 v[228:229], s[48:49], 0, v[128:129]
	s_mov_b32 m0, s90
	s_nop 0
	global_load_lds_dwordx4 v[228:229], off
	s_waitcnt vmcnt(8)
	s_waitcnt lgkmcnt(0)
	s_barrier
	s_setprio 1
	s_waitcnt lgkmcnt(0)
	v_mfma_f32_16x16x32_bf16 v[124:127], v[136:139], v[180:183], v[124:127]
	v_mfma_f32_16x16x32_bf16 v[120:123], v[154:157], v[180:183], v[120:123]
	v_mfma_f32_16x16x32_bf16 v[108:111], v[136:139], v[188:191], v[108:111]
	v_mfma_f32_16x16x32_bf16 v[104:107], v[154:157], v[188:191], v[104:107]
	v_mfma_f32_16x16x32_bf16 v[92:95], v[136:139], v[196:199], v[92:95]
	v_mfma_f32_16x16x32_bf16 v[88:91], v[154:157], v[196:199], v[88:91]
	v_mfma_f32_16x16x32_bf16 v[76:79], v[136:139], v[212:215], v[76:79]
	v_mfma_f32_16x16x32_bf16 v[72:75], v[154:157], v[212:215], v[72:75]
	v_mfma_f32_16x16x32_bf16 v[124:127], v[146:149], v[184:187], v[124:127]
	v_mfma_f32_16x16x32_bf16 v[120:123], v[160:163], v[184:187], v[120:123]
	v_mfma_f32_16x16x32_bf16 v[108:111], v[146:149], v[192:195], v[108:111]
	v_mfma_f32_16x16x32_bf16 v[104:107], v[160:163], v[192:195], v[104:107]
	v_mfma_f32_16x16x32_bf16 v[92:95], v[146:149], v[208:211], v[92:95]
	v_mfma_f32_16x16x32_bf16 v[88:91], v[160:163], v[208:211], v[88:91]
	v_mfma_f32_16x16x32_bf16 v[76:79], v[146:149], v[216:219], v[76:79]
	v_mfma_f32_16x16x32_bf16 v[72:75], v[160:163], v[216:219], v[72:75]
	s_setprio 0
	s_setprio 1
	v_mfma_f32_16x16x32_bf16 v[116:119], v[164:167], v[180:183], v[116:119]
	v_mfma_f32_16x16x32_bf16 v[112:115], v[172:175], v[180:183], v[112:115]
	v_mfma_f32_16x16x32_bf16 v[100:103], v[164:167], v[188:191], v[100:103]
	v_mfma_f32_16x16x32_bf16 v[96:99], v[172:175], v[188:191], v[96:99]
	v_mfma_f32_16x16x32_bf16 v[84:87], v[164:167], v[196:199], v[84:87]
	v_mfma_f32_16x16x32_bf16 v[80:83], v[172:175], v[196:199], v[80:83]
	v_mfma_f32_16x16x32_bf16 v[68:71], v[164:167], v[212:215], v[68:71]
	v_mfma_f32_16x16x32_bf16 v[64:67], v[172:175], v[212:215], v[64:67]
	v_mfma_f32_16x16x32_bf16 v[116:119], v[168:171], v[184:187], v[116:119]
	v_mfma_f32_16x16x32_bf16 v[112:115], v[176:179], v[184:187], v[112:115]
	v_mfma_f32_16x16x32_bf16 v[100:103], v[168:171], v[192:195], v[100:103]
	v_mfma_f32_16x16x32_bf16 v[96:99], v[176:179], v[192:195], v[96:99]
	v_mfma_f32_16x16x32_bf16 v[84:87], v[168:171], v[208:211], v[84:87]
	v_mfma_f32_16x16x32_bf16 v[80:83], v[176:179], v[208:211], v[80:83]
	v_mfma_f32_16x16x32_bf16 v[68:71], v[168:171], v[216:219], v[68:71]
	v_mfma_f32_16x16x32_bf16 v[64:67], v[176:179], v[216:219], v[64:67]
	s_setprio 0
	s_barrier
; #define PG8_STAGE(bufoff, gbase, voff) do { _Pragma("unroll") for (int _i = 0; _i < 2; ++_i) \
;         __builtin_amdgcn_global_load_lds((const unsigned*)((const char*)(gbase) + (voff)[_i]), (PG8_LAS unsigned*)(lds + (bufoff) + ldsw + _i * 8192), 16, 0, 0); } while (0)
; #define PG8_LDA(dst, b, h) do { _Pragma("unroll") for (int m = 0; m < 4; ++m) _Pragma("unroll") for (int k = 0; k < 2; ++k) dst[m][k] = *(const PG8_LAS bf16x8*)(lds + PG8_SA(b, h) + aoff + m * 2048 + k * 1024); } while (0)
; #define PG8_MMA(ai, bj, At, Bt) do { __builtin_amdgcn_s_setprio(1); _Pragma("unroll") for (int m = 0; m < 4; ++m) _Pragma("unroll") for (int n = 0; n < 2; ++n) _Pragma("unroll") for (int k = 0; k < 2; ++k) \
;         acc[ai][bj][m][n] = __builtin_amdgcn_mfma_f32_16x16x32_bf16(Bt[n][k], At[m][k], acc[ai][bj][m][n], 0, 0, 0); __builtin_amdgcn_s_setprio(0); } while (0)
; #define PG8_WAIT_V(n) asm volatile("s_waitcnt vmcnt(" #n ")" ::: "memory")
; #define PG8_WAIT_L(n) asm volatile("s_waitcnt lgkmcnt(" #n ")" ::: "memory")
; #define PG8_BAR __builtin_amdgcn_s_barrier()
; #define PG8_SCHED __builtin_amdgcn_sched_barrier(0)
; template <class Epi, class Sched, bool ALIGN_EPI = false, bool SP2 = false>
; __device__ __forceinline__ void gemm_phase(PG8_LAS unsigned char* lds, const Gemm g, const Sched& S, const Epi& E) {
;     ...
;         for (int t = 0; t < nt; t += 2) {
;     ...
;             PG8_LDA(At, 1, 1); PG8_STAGE(PG8_SB(1, 0), b3, voffB); PG8_STAGE(PG8_SB(1, 1), b3 + hstep, voffB); PG8_STAGE(PG8_SA(1, 0), a3, voffA);
;             PG8_WAIT_V(8); PG8_WAIT_L(0); PG8_BAR; PG8_MMA(1, 0, At, B0); PG8_MMA(1, 1, At, B1); PG8_BAR; PG8_SCHED;
	s_add_i32 s48, s61, s71
	v_lshl_add_u64 v[220:221], v[220:221], 0, s[84:85]
	s_mov_b32 m0, s48
	ds_read_b128 v[180:183], v158 offset:49152
	ds_read_b128 v[184:187], v158 offset:50176
	ds_read_b128 v[188:191], v158 offset:51200
	ds_read_b128 v[192:195], v158 offset:52224
	ds_read_b128 v[196:199], v158 offset:53248
	ds_read_b128 v[208:211], v158 offset:54272
	ds_read_b128 v[212:215], v158 offset:55296
	ds_read_b128 v[216:219], v158 offset:56320
	global_load_lds_dwordx4 v[220:221], off
	s_add_i32 m0, s48, 0x2000
	s_add_u32 s48, s62, 0x80080
	v_lshl_add_u64 v[220:221], v[222:223], 0, s[84:85]
	s_addc_u32 s49, s63, 0
	s_add_i32 s61, s78, s71
	global_load_lds_dwordx4 v[220:221], off
	v_lshl_add_u64 v[220:221], s[48:49], 0, v[130:131]
	s_mov_b32 m0, s61
	s_nop 0
	global_load_lds_dwordx4 v[220:221], off
	v_lshl_add_u64 v[220:221], s[48:49], 0, v[128:129]
	s_add_i32 m0, s61, 0x2000
	s_nop 0
	global_load_lds_dwordx4 v[220:221], off
	s_waitcnt vmcnt(4)
	s_waitcnt lgkmcnt(0)
	s_barrier
	s_setprio 1
	s_waitcnt lgkmcnt(0)
	v_mfma_f32_16x16x32_bf16 v[60:63], v[136:139], v[180:183], v[60:63]
	v_mfma_f32_16x16x32_bf16 v[56:59], v[154:157], v[180:183], v[56:59]
	v_mfma_f32_16x16x32_bf16 v[44:47], v[136:139], v[188:191], v[44:47]
	v_mfma_f32_16x16x32_bf16 v[40:43], v[154:157], v[188:191], v[40:43]
	v_mfma_f32_16x16x32_bf16 v[28:31], v[136:139], v[196:199], v[28:31]
	v_mfma_f32_16x16x32_bf16 v[24:27], v[154:157], v[196:199], v[24:27]
	v_mfma_f32_16x16x32_bf16 v[12:15], v[136:139], v[212:215], v[12:15]
	v_mfma_f32_16x16x32_bf16 v[8:11], v[154:157], v[212:215], v[8:11]
	v_mfma_f32_16x16x32_bf16 v[60:63], v[146:149], v[184:187], v[60:63]
	v_mfma_f32_16x16x32_bf16 v[56:59], v[160:163], v[184:187], v[56:59]
	v_mfma_f32_16x16x32_bf16 v[44:47], v[146:149], v[192:195], v[44:47]
	v_mfma_f32_16x16x32_bf16 v[40:43], v[160:163], v[192:195], v[40:43]
	v_mfma_f32_16x16x32_bf16 v[28:31], v[146:149], v[208:211], v[28:31]
	v_mfma_f32_16x16x32_bf16 v[24:27], v[160:163], v[208:211], v[24:27]
	v_mfma_f32_16x16x32_bf16 v[12:15], v[146:149], v[216:219], v[12:15]
	v_mfma_f32_16x16x32_bf16 v[8:11], v[160:163], v[216:219], v[8:11]
	s_setprio 0
	s_setprio 1
	v_mfma_f32_16x16x32_bf16 v[52:55], v[164:167], v[180:183], v[52:55]
	v_mfma_f32_16x16x32_bf16 v[48:51], v[172:175], v[180:183], v[48:51]
	v_mfma_f32_16x16x32_bf16 v[36:39], v[164:167], v[188:191], v[36:39]
	v_mfma_f32_16x16x32_bf16 v[32:35], v[172:175], v[188:191], v[32:35]
	v_mfma_f32_16x16x32_bf16 v[20:23], v[164:167], v[196:199], v[20:23]
	v_mfma_f32_16x16x32_bf16 v[16:19], v[172:175], v[196:199], v[16:19]
	v_mfma_f32_16x16x32_bf16 v[4:7], v[164:167], v[212:215], v[4:7]
	v_mfma_f32_16x16x32_bf16 v[0:3], v[172:175], v[212:215], v[0:3]
	v_mfma_f32_16x16x32_bf16 v[52:55], v[168:171], v[184:187], v[52:55]
	v_mfma_f32_16x16x32_bf16 v[48:51], v[176:179], v[184:187], v[48:51]
	v_mfma_f32_16x16x32_bf16 v[36:39], v[168:171], v[192:195], v[36:39]
	v_mfma_f32_16x16x32_bf16 v[32:35], v[176:179], v[192:195], v[32:35]
	v_mfma_f32_16x16x32_bf16 v[20:23], v[168:171], v[208:211], v[20:23]
	v_mfma_f32_16x16x32_bf16 v[16:19], v[176:179], v[208:211], v[16:19]
	v_mfma_f32_16x16x32_bf16 v[4:7], v[168:171], v[216:219], v[4:7]
	v_mfma_f32_16x16x32_bf16 v[0:3], v[176:179], v[216:219], v[0:3]
	s_setprio 0
	s_barrier
	s_add_i32 s56, s56, 2
	s_add_u32 s30, s30, 0x100
	s_addc_u32 s31, s31, 0
	s_cmp_gt_u32 s56, 29
	s_mov_b64 s[48:49], s[54:55]
	s_cbranch_scc0 .LBB0_816
	s_and_b64 vcc, exec, s[18:19]
	s_cbranch_vccz .LBB0_819
	s_barrier

;     __host__ __device__ bool next(int i, Unit& u) const { const int L = i * G + c; if (L >= nunits) return false; u.pm = pm; u.pn = L & 7; u.ko = (L >> 3) * klen; return true; }
; #define PG8_STAGE(bufoff, gbase, voff) do { _Pragma("unroll") for (int _i = 0; _i < 2; ++_i) \
;         __builtin_amdgcn_global_load_lds((const unsigned*)((const char*)(gbase) + (voff)[_i]), (PG8_LAS unsigned*)(lds + (bufoff) + ldsw + _i * 8192), 16, 0, 0); } while (0)
; #define PG8_LDA(dst, b, h) do { _Pragma("unroll") for (int m = 0; m < 4; ++m) _Pragma("unroll") for (int k = 0; k < 2; ++k) dst[m][k] = *(const PG8_LAS bf16x8*)(lds + PG8_SA(b, h) + aoff + m * 2048 + k * 1024); } while (0)
; #define PG8_LDB(dst, b, h) do { _Pragma("unroll") for (int n = 0; n < 2; ++n) _Pragma("unroll") for (int k = 0; k < 2; ++k) dst[n][k] = *(const PG8_LAS bf16x8*)(lds + PG8_SB(b, h) + boff + n * 2048 + k * 1024); } while (0)
; #define PG8_WAIT_V(n) asm volatile("s_waitcnt vmcnt(" #n ")" ::: "memory")
; template <class Epi, class Sched, bool ALIGN_EPI = false, bool SP2 = false>
; __device__ __forceinline__ void gemm_phase(PG8_LAS unsigned char* lds, const Gemm g, const Sched& S, const Epi& E) {
;     ...
;         const bool has_next = S.next(ui + 1, nxt);
;         const char* nA = has_next ? (const char*)g.A + (size_t)nxt.pm * tstep + (size_t)nxt.ko * 2 : cA; const char* nB = has_next ? (const char*)g.Bt + (size_t)nxt.pn * tstep + (size_t)nxt.ko * 2 : cB;
;         for (int t = 0; t < nt; t += 2) {
;             const bool last = (t == nt - 2);
;             const char* a1 = cA + (size_t)(t + 1) * kstep;
;             const char* a2 = last ? nA : cA + (size_t)(t + 2) * kstep; const char* b2 = last ? nB : cB + (size_t)(t + 2) * kstep;
;             const char* a3 = a2 + kstep; const char* b3 = b2 + kstep;
;             if (last && has_next) S.a_ready(nxt);
;             if constexpr (SP2) {
;             PG8_LDB(B0, 0, 0); PG8_LDB(B1, 0, 1); PG8_SCHED; PG8_LDA(At, 0, 0); PG8_STAGE(PG8_SA(1, 1), a1 + hstep, voffA);
;             PG8_WAIT_V(8); PG8_WAIT_L(0); PG8_BAR; PG8_MMA(0, 0, At, B0); PG8_MMA(0, 1, At, B1); PG8_BAR; PG8_SCHED;
;     ...
;         for (int a = 0; a < 2; ++a)
; #pragma unroll
;             for (int b = 0; b < 2; ++b)
; #pragma unroll
;                 for (int m = 0; m < 4; ++m)
; #pragma unroll
;                     for (int n = 0; n < 2; ++n) acc[a][b][m][n] = (f32x4){0.f, 0.f, 0.f, 0.f};
.LBB0_1145:
	s_ashr_i32 s23, s22, 31
	s_lshl_b64 s[26:27], s[22:23], 22
	s_add_u32 s26, s70, s26
	s_addc_u32 s27, s71, s27
	s_and_b64 s[30:31], s[8:9], exec
	s_cselect_b32 s23, s27, s49
	s_cselect_b32 s30, s26, s48
	s_ashr_i32 s19, s18, 31
	s_lshl_b64 s[36:37], s[18:19], 22
	s_add_u32 s36, s57, s36
	s_addc_u32 s37, s67, s37
	s_and_b64 s[62:63], s[8:9], exec
	s_cselect_b32 s19, s37, s55
	s_cselect_b32 s31, s36, s54
	s_add_u32 s56, s54, 0x100
	v_mov_b32_e32 v0, 0
	s_addc_u32 s95, s55, 0
	s_mov_b32 s96, -2
	v_mov_b32_e32 v1, v0
	v_mov_b32_e32 v2, v0
	v_mov_b32_e32 v3, v0
	v_mov_b32_e32 v4, v0
	v_mov_b32_e32 v5, v0
	v_mov_b32_e32 v6, v0
	v_mov_b32_e32 v7, v0
	v_mov_b32_e32 v16, v0
	v_mov_b32_e32 v17, v0
	v_mov_b32_e32 v18, v0
	v_mov_b32_e32 v19, v0
	v_mov_b32_e32 v20, v0
	v_mov_b32_e32 v21, v0
	v_mov_b32_e32 v22, v0
	v_mov_b32_e32 v23, v0
	v_mov_b32_e32 v32, v0
	v_mov_b32_e32 v33, v0
	v_mov_b32_e32 v34, v0
	v_mov_b32_e32 v35, v0
	v_mov_b32_e32 v36, v0
	v_mov_b32_e32 v37, v0
	v_mov_b32_e32 v38, v0
	v_mov_b32_e32 v39, v0
	v_mov_b32_e32 v48, v0
	v_mov_b32_e32 v49, v0
	v_mov_b32_e32 v50, v0
	v_mov_b32_e32 v51, v0
	v_mov_b32_e32 v52, v0
	v_mov_b32_e32 v53, v0
	v_mov_b32_e32 v54, v0
	v_mov_b32_e32 v55, v0
	v_mov_b32_e32 v8, v0
	v_mov_b32_e32 v9, v0
	v_mov_b32_e32 v10, v0
	v_mov_b32_e32 v11, v0
	v_mov_b32_e32 v12, v0
	v_mov_b32_e32 v13, v0
	v_mov_b32_e32 v14, v0
	v_mov_b32_e32 v15, v0
	v_mov_b32_e32 v24, v0
	v_mov_b32_e32 v25, v0
	v_mov_b32_e32 v26, v0
	v_mov_b32_e32 v27, v0
	v_mov_b32_e32 v28, v0
	v_mov_b32_e32 v29, v0
	v_mov_b32_e32 v30, v0
	v_mov_b32_e32 v31, v0
	v_mov_b32_e32 v40, v0
	v_mov_b32_e32 v41, v0
	v_mov_b32_e32 v42, v0
	v_mov_b32_e32 v43, v0
	v_mov_b32_e32 v44, v0
	v_mov_b32_e32 v45, v0
	v_mov_b32_e32 v46, v0
	v_mov_b32_e32 v47, v0
	v_mov_b32_e32 v56, v0
	v_mov_b32_e32 v57, v0
	v_mov_b32_e32 v58, v0
	v_mov_b32_e32 v59, v0
	v_mov_b32_e32 v60, v0
	v_mov_b32_e32 v61, v0
	v_mov_b32_e32 v62, v0
	v_mov_b32_e32 v63, v0
	v_mov_b32_e32 v64, v0
	v_mov_b32_e32 v65, v0
	v_mov_b32_e32 v66, v0
	v_mov_b32_e32 v67, v0
	v_mov_b32_e32 v68, v0
	v_mov_b32_e32 v69, v0
	v_mov_b32_e32 v70, v0
	v_mov_b32_e32 v71, v0
	v_mov_b32_e32 v80, v0
	v_mov_b32_e32 v81, v0
	v_mov_b32_e32 v82, v0
	v_mov_b32_e32 v83, v0
	v_mov_b32_e32 v84, v0
	v_mov_b32_e32 v85, v0
	v_mov_b32_e32 v86, v0
	v_mov_b32_e32 v87, v0
	v_mov_b32_e32 v96, v0
	v_mov_b32_e32 v97, v0
	v_mov_b32_e32 v98, v0
	v_mov_b32_e32 v99, v0
	v_mov_b32_e32 v100, v0
	v_mov_b32_e32 v101, v0
	v_mov_b32_e32 v102, v0
	v_mov_b32_e32 v103, v0
	v_mov_b32_e32 v112, v0
	v_mov_b32_e32 v113, v0
	v_mov_b32_e32 v114, v0
	v_mov_b32_e32 v115, v0
	v_mov_b32_e32 v116, v0
	v_mov_b32_e32 v117, v0
	v_mov_b32_e32 v118, v0
	v_mov_b32_e32 v119, v0
	v_mov_b32_e32 v72, v0
	v_mov_b32_e32 v73, v0
	v_mov_b32_e32 v74, v0
	v_mov_b32_e32 v75, v0
	v_mov_b32_e32 v76, v0
	v_mov_b32_e32 v77, v0
	v_mov_b32_e32 v78, v0
	v_mov_b32_e32 v79, v0
	v_mov_b32_e32 v88, v0
	v_mov_b32_e32 v89, v0
	v_mov_b32_e32 v90, v0
	v_mov_b32_e32 v91, v0
	v_mov_b32_e32 v92, v0
	v_mov_b32_e32 v93, v0
	v_mov_b32_e32 v94, v0
	v_mov_b32_e32 v95, v0
	v_mov_b32_e32 v104, v0
	v_mov_b32_e32 v105, v0
	v_mov_b32_e32 v106, v0
	v_mov_b32_e32 v107, v0
	v_mov_b32_e32 v108, v0
	v_mov_b32_e32 v109, v0
	v_mov_b32_e32 v110, v0
	v_mov_b32_e32 v111, v0
	v_mov_b32_e32 v120, v0
	v_mov_b32_e32 v121, v0
	v_mov_b32_e32 v122, v0
	v_mov_b32_e32 v123, v0
	v_mov_b32_e32 v124, v0
	v_mov_b32_e32 v125, v0
	v_mov_b32_e32 v126, v0
	v_mov_b32_e32 v127, v0
	v_lshl_add_u64 v[224:225], s[48:49], 0, v[130:131]
	v_lshl_add_u64 v[226:227], s[48:49], 0, v[128:129]
.LBB0_1146:
	s_add_u32 s54, s48, 0x100
	s_addc_u32 s55, s49, 0
	s_add_i32 s43, 0, 0x10000
	s_cmpk_eq_i32 s96, 0x7c
	s_cselect_b32 s65, s23, s55
	s_cselect_b32 s64, s30, s54
	v_add_u32_e32 v140, s43, v151
	s_cselect_b32 s63, s19, s95
	s_cselect_b32 s62, s31, s56
	s_add_i32 s61, 0, 0x14000
	ds_read_b128 v[136:139], v140
	ds_read_b128 v[146:149], v140 offset:1024
	ds_read_b128 v[154:157], v140 offset:2048
	ds_read_b128 v[160:163], v140 offset:3072
	v_add_u32_e32 v140, s61, v151
	ds_read_b128 v[164:167], v140
	ds_read_b128 v[168:171], v140 offset:1024
	ds_read_b128 v[172:175], v140 offset:2048
	ds_read_b128 v[176:179], v140 offset:3072
	v_lshl_add_u64 v[220:221], s[48:49], 0, v[132:133]
	s_add_i32 m0, s73, 0xc000
	ds_read_b128 v[180:183], v158
	ds_read_b128 v[184:187], v158 offset:1024
	ds_read_b128 v[188:191], v158 offset:2048
	ds_read_b128 v[192:195], v158 offset:3072
	ds_read_b128 v[196:199], v158 offset:4096
	ds_read_b128 v[208:211], v158 offset:5120
	ds_read_b128 v[212:215], v158 offset:6144
	ds_read_b128 v[216:219], v158 offset:7168
	global_load_lds_dwordx4 v[220:221], off
	v_lshl_add_u64 v[220:221], s[48:49], 0, v[134:135]
	s_add_i32 m0, s73, 0xe000
	s_nop 0
	global_load_lds_dwordx4 v[220:221], off
	v_lshl_add_u64 v[220:221], v[224:225], 0, s[84:85]
	s_mov_b32 m0, s92
	s_nop 0
	global_load_lds_dwordx4 v[220:221], off
	v_lshl_add_u64 v[220:221], v[226:227], 0, s[84:85]
	s_mov_b32 m0, s93
	s_nop 0
	global_load_lds_dwordx4 v[220:221], off
	s_waitcnt vmcnt(8)
	s_waitcnt lgkmcnt(0)
	s_barrier
; #define PG8_STAGE(bufoff, gbase, voff) do { _Pragma("unroll") for (int _i = 0; _i < 2; ++_i) \
;         __builtin_amdgcn_global_load_lds((const unsigned*)((const char*)(gbase) + (voff)[_i]), (PG8_LAS unsigned*)(lds + (bufoff) + ldsw + _i * 8192), 16, 0, 0); } while (0)
; #define PG8_LDA(dst, b, h) do { _Pragma("unroll") for (int m = 0; m < 4; ++m) _Pragma("unroll") for (int k = 0; k < 2; ++k) dst[m][k] = *(const PG8_LAS bf16x8*)(lds + PG8_SA(b, h) + aoff + m * 2048 + k * 1024); } while (0)
; #define PG8_LDB(dst, b, h) do { _Pragma("unroll") for (int n = 0; n < 2; ++n) _Pragma("unroll") for (int k = 0; k < 2; ++k) dst[n][k] = *(const PG8_LAS bf16x8*)(lds + PG8_SB(b, h) + boff + n * 2048 + k * 1024); } while (0)
; #define PG8_MMA(ai, bj, At, Bt) do { __builtin_amdgcn_s_setprio(1); _Pragma("unroll") for (int m = 0; m < 4; ++m) _Pragma("unroll") for (int n = 0; n < 2; ++n) _Pragma("unroll") for (int k = 0; k < 2; ++k) \
;         acc[ai][bj][m][n] = __builtin_amdgcn_mfma_f32_16x16x32_bf16(Bt[n][k], At[m][k], acc[ai][bj][m][n], 0, 0, 0); __builtin_amdgcn_s_setprio(0); } while (0)
; #define PG8_WAIT_V(n) asm volatile("s_waitcnt vmcnt(" #n ")" ::: "memory")
; #define PG8_WAIT_L(n) asm volatile("s_waitcnt lgkmcnt(" #n ")" ::: "memory")
; #define PG8_BAR __builtin_amdgcn_s_barrier()
; #define PG8_SCHED __builtin_amdgcn_sched_barrier(0)
; template <class Epi, class Sched, bool ALIGN_EPI = false, bool SP2 = false>
; __device__ __forceinline__ void gemm_phase(PG8_LAS unsigned char* lds, const Gemm g, const Sched& S, const Epi& E) {
;     ...
;             PG8_LDB(B0, 0, 0); PG8_LDB(B1, 0, 1); PG8_SCHED; PG8_LDA(At, 0, 0); PG8_STAGE(PG8_SA(1, 1), a1 + hstep, voffA);
;             PG8_WAIT_V(8); PG8_WAIT_L(0); PG8_BAR; PG8_MMA(0, 0, At, B0); PG8_MMA(0, 1, At, B1); PG8_BAR; PG8_SCHED;
;             PG8_LDA(At, 0, 1); PG8_STAGE(PG8_SB(0, 0), b2, voffB); PG8_STAGE(PG8_SB(0, 1), b2 + hstep, voffB); PG8_STAGE(PG8_SA(0, 0), a2, voffA);
;             PG8_WAIT_V(8); PG8_WAIT_L(0); PG8_BAR; PG8_MMA(1, 0, At, B0); PG8_MMA(1, 1, At, B1); PG8_BAR; PG8_SCHED;
	s_setprio 1
	s_waitcnt lgkmcnt(0)
	v_mfma_f32_16x16x32_bf16 v[124:127], v[136:139], v[180:183], v[124:127]
	v_mfma_f32_16x16x32_bf16 v[120:123], v[154:157], v[180:183], v[120:123]
	v_mfma_f32_16x16x32_bf16 v[108:111], v[136:139], v[188:191], v[108:111]
	v_mfma_f32_16x16x32_bf16 v[104:107], v[154:157], v[188:191], v[104:107]
	v_mfma_f32_16x16x32_bf16 v[92:95], v[136:139], v[196:199], v[92:95]
	v_mfma_f32_16x16x32_bf16 v[88:91], v[154:157], v[196:199], v[88:91]
	v_mfma_f32_16x16x32_bf16 v[76:79], v[136:139], v[212:215], v[76:79]
	v_mfma_f32_16x16x32_bf16 v[72:75], v[154:157], v[212:215], v[72:75]
	v_mfma_f32_16x16x32_bf16 v[124:127], v[146:149], v[184:187], v[124:127]
	v_mfma_f32_16x16x32_bf16 v[120:123], v[160:163], v[184:187], v[120:123]
	v_mfma_f32_16x16x32_bf16 v[108:111], v[146:149], v[192:195], v[108:111]
	v_mfma_f32_16x16x32_bf16 v[104:107], v[160:163], v[192:195], v[104:107]
	v_mfma_f32_16x16x32_bf16 v[92:95], v[146:149], v[208:211], v[92:95]
	v_mfma_f32_16x16x32_bf16 v[88:91], v[160:163], v[208:211], v[88:91]
	v_mfma_f32_16x16x32_bf16 v[76:79], v[146:149], v[216:219], v[76:79]
	v_mfma_f32_16x16x32_bf16 v[72:75], v[160:163], v[216:219], v[72:75]
	s_setprio 0
	s_setprio 1
	v_mfma_f32_16x16x32_bf16 v[116:119], v[164:167], v[180:183], v[116:119]
	v_mfma_f32_16x16x32_bf16 v[112:115], v[172:175], v[180:183], v[112:115]
	v_mfma_f32_16x16x32_bf16 v[100:103], v[164:167], v[188:191], v[100:103]
	v_mfma_f32_16x16x32_bf16 v[96:99], v[172:175], v[188:191], v[96:99]
	v_mfma_f32_16x16x32_bf16 v[84:87], v[164:167], v[196:199], v[84:87]
	v_mfma_f32_16x16x32_bf16 v[80:83], v[172:175], v[196:199], v[80:83]
	v_mfma_f32_16x16x32_bf16 v[68:71], v[164:167], v[212:215], v[68:71]
	v_mfma_f32_16x16x32_bf16 v[64:67], v[172:175], v[212:215], v[64:67]
	v_mfma_f32_16x16x32_bf16 v[116:119], v[168:171], v[184:187], v[116:119]
	v_mfma_f32_16x16x32_bf16 v[112:115], v[176:179], v[184:187], v[112:115]
	v_mfma_f32_16x16x32_bf16 v[100:103], v[168:171], v[192:195], v[100:103]
	v_mfma_f32_16x16x32_bf16 v[96:99], v[176:179], v[192:195], v[96:99]
	v_mfma_f32_16x16x32_bf16 v[84:87], v[168:171], v[208:211], v[84:87]
	v_mfma_f32_16x16x32_bf16 v[80:83], v[176:179], v[208:211], v[80:83]
	v_mfma_f32_16x16x32_bf16 v[68:71], v[168:171], v[216:219], v[68:71]
	v_mfma_f32_16x16x32_bf16 v[64:67], v[176:179], v[216:219], v[64:67]
	s_setprio 0
	s_barrier
	s_add_i32 s43, s43, s72
	v_lshl_add_u64 v[220:221], s[62:63], 0, v[130:131]
	s_mov_b32 m0, s43
	ds_read_b128 v[180:183], v158 offset:16384
	ds_read_b128 v[184:187], v158 offset:17408
	ds_read_b128 v[188:191], v158 offset:18432
	ds_read_b128 v[192:195], v158 offset:19456
	ds_read_b128 v[196:199], v158 offset:20480
	ds_read_b128 v[208:211], v158 offset:21504
	ds_read_b128 v[212:215], v158 offset:22528
	ds_read_b128 v[216:219], v158 offset:23552
	global_load_lds_dwordx4 v[220:221], off
	s_add_i32 m0, s43, 0x2000
	s_add_u32 s48, s62, 0x200000
	v_lshl_add_u64 v[222:223], s[62:63], 0, v[128:129]
	s_addc_u32 s49, s63, 0
	s_add_i32 s43, s61, s72
	global_load_lds_dwordx4 v[222:223], off
	v_lshl_add_u64 v[224:225], s[48:49], 0, v[130:131]
	s_mov_b32 m0, s43
	global_load_lds_dwordx4 v[224:225], off
	v_lshl_add_u64 v[224:225], s[48:49], 0, v[128:129]
	s_add_i32 m0, s43, 0x2000
	s_nop 0
	global_load_lds_dwordx4 v[224:225], off
	s_waitcnt vmcnt(4)
	s_waitcnt lgkmcnt(0)
	s_barrier
	s_setprio 1
	s_waitcnt lgkmcnt(0)
	v_mfma_f32_16x16x32_bf16 v[60:63], v[136:139], v[180:183], v[60:63]
	v_mfma_f32_16x16x32_bf16 v[56:59], v[154:157], v[180:183], v[56:59]
	v_mfma_f32_16x16x32_bf16 v[44:47], v[136:139], v[188:191], v[44:47]
	v_mfma_f32_16x16x32_bf16 v[40:43], v[154:157], v[188:191], v[40:43]
	v_mfma_f32_16x16x32_bf16 v[28:31], v[136:139], v[196:199], v[28:31]
	v_mfma_f32_16x16x32_bf16 v[24:27], v[154:157], v[196:199], v[24:27]
	v_mfma_f32_16x16x32_bf16 v[12:15], v[136:139], v[212:215], v[12:15]
	v_mfma_f32_16x16x32_bf16 v[8:11], v[154:157], v[212:215], v[8:11]
	v_mfma_f32_16x16x32_bf16 v[60:63], v[146:149], v[184:187], v[60:63]
	v_mfma_f32_16x16x32_bf16 v[56:59], v[160:163], v[184:187], v[56:59]
	v_mfma_f32_16x16x32_bf16 v[44:47], v[146:149], v[192:195], v[44:47]
	v_mfma_f32_16x16x32_bf16 v[40:43], v[160:163], v[192:195], v[40:43]
	v_mfma_f32_16x16x32_bf16 v[28:31], v[146:149], v[208:211], v[28:31]
	v_mfma_f32_16x16x32_bf16 v[24:27], v[160:163], v[208:211], v[24:27]
	v_mfma_f32_16x16x32_bf16 v[12:15], v[146:149], v[216:219], v[12:15]
	v_mfma_f32_16x16x32_bf16 v[8:11], v[160:163], v[216:219], v[8:11]
	s_setprio 0
	s_setprio 1
	v_mfma_f32_16x16x32_bf16 v[52:55], v[164:167], v[180:183], v[52:55]
	v_mfma_f32_16x16x32_bf16 v[48:51], v[172:175], v[180:183], v[48:51]
	v_mfma_f32_16x16x32_bf16 v[36:39], v[164:167], v[188:191], v[36:39]
	v_mfma_f32_16x16x32_bf16 v[32:35], v[172:175], v[188:191], v[32:35]
	v_mfma_f32_16x16x32_bf16 v[20:23], v[164:167], v[196:199], v[20:23]
	v_mfma_f32_16x16x32_bf16 v[16:19], v[172:175], v[196:199], v[16:19]
	v_mfma_f32_16x16x32_bf16 v[4:7], v[164:167], v[212:215], v[4:7]
	v_mfma_f32_16x16x32_bf16 v[0:3], v[172:175], v[212:215], v[0:3]
	v_mfma_f32_16x16x32_bf16 v[52:55], v[168:171], v[184:187], v[52:55]
	v_mfma_f32_16x16x32_bf16 v[48:51], v[176:179], v[184:187], v[48:51]
	v_mfma_f32_16x16x32_bf16 v[36:39], v[168:171], v[192:195], v[36:39]
	v_mfma_f32_16x16x32_bf16 v[32:35], v[176:179], v[192:195], v[32:35]
	v_mfma_f32_16x16x32_bf16 v[20:23], v[168:171], v[208:211], v[20:23]
	v_mfma_f32_16x16x32_bf16 v[16:19], v[176:179], v[208:211], v[16:19]
	v_mfma_f32_16x16x32_bf16 v[4:7], v[168:171], v[216:219], v[4:7]
	v_mfma_f32_16x16x32_bf16 v[0:3], v[176:179], v[216:219], v[0:3]
	s_setprio 0
	s_barrier
; #define PG8_STAGE(bufoff, gbase, voff) do { _Pragma("unroll") for (int _i = 0; _i < 2; ++_i) \
;         __builtin_amdgcn_global_load_lds((const unsigned*)((const char*)(gbase) + (voff)[_i]), (PG8_LAS unsigned*)(lds + (bufoff) + ldsw + _i * 8192), 16, 0, 0); } while (0)
; #define PG8_LDA(dst, b, h) do { _Pragma("unroll") for (int m = 0; m < 4; ++m) _Pragma("unroll") for (int k = 0; k < 2; ++k) dst[m][k] = *(const PG8_LAS bf16x8*)(lds + PG8_SA(b, h) + aoff + m * 2048 + k * 1024); } while (0)
; #define PG8_LDB(dst, b, h) do { _Pragma("unroll") for (int n = 0; n < 2; ++n) _Pragma("unroll") for (int k = 0; k < 2; ++k) dst[n][k] = *(const PG8_LAS bf16x8*)(lds + PG8_SB(b, h) + boff + n * 2048 + k * 1024); } while (0)
; #define PG8_MMA(ai, bj, At, Bt) do { __builtin_amdgcn_s_setprio(1); _Pragma("unroll") for (int m = 0; m < 4; ++m) _Pragma("unroll") for (int n = 0; n < 2; ++n) _Pragma("unroll") for (int k = 0; k < 2; ++k) \
;         acc[ai][bj][m][n] = __builtin_amdgcn_mfma_f32_16x16x32_bf16(Bt[n][k], At[m][k], acc[ai][bj][m][n], 0, 0, 0); __builtin_amdgcn_s_setprio(0); } while (0)
; #define PG8_WAIT_V(n) asm volatile("s_waitcnt vmcnt(" #n ")" ::: "memory")
; #define PG8_WAIT_L(n) asm volatile("s_waitcnt lgkmcnt(" #n ")" ::: "memory")
; #define PG8_BAR __builtin_amdgcn_s_barrier()
; #define PG8_SCHED __builtin_amdgcn_sched_barrier(0)
; template <class Epi, class Sched, bool ALIGN_EPI = false, bool SP2 = false>
; __device__ __forceinline__ void gemm_phase(PG8_LAS unsigned char* lds, const Gemm g, const Sched& S, const Epi& E) {
;     ...
;             PG8_LDB(B0, 1, 0); PG8_LDB(B1, 1, 1); PG8_SCHED; PG8_LDA(At, 1, 0); PG8_STAGE(PG8_SA(0, 1), a2 + hstep, voffA);
;             PG8_WAIT_V(8); PG8_WAIT_L(0); PG8_BAR; PG8_MMA(0, 0, At, B0); PG8_MMA(0, 1, At, B1); PG8_BAR; PG8_SCHED;
	s_add_i32 s43, 0, 0x18000
	v_add_u32_e32 v140, s43, v151
	s_add_i32 s61, 0, 0x1c000
	ds_read_b128 v[136:139], v140
	ds_read_b128 v[146:149], v140 offset:1024
	ds_read_b128 v[154:157], v140 offset:2048
	ds_read_b128 v[160:163], v140 offset:3072
	v_add_u32_e32 v140, s61, v151
	ds_read_b128 v[164:167], v140
	ds_read_b128 v[168:171], v140 offset:1024
	ds_read_b128 v[172:175], v140 offset:2048
	ds_read_b128 v[176:179], v140 offset:3072
	v_lshl_add_u64 v[224:225], s[64:65], 0, v[130:131]
	s_mov_b32 m0, s73
	s_nop 0
	global_load_lds_dwordx4 v[224:225], off
	v_lshl_add_u64 v[226:227], s[64:65], 0, v[128:129]
	s_mov_b32 m0, s76
	s_nop 0
	global_load_lds_dwordx4 v[226:227], off
	s_add_u32 s48, s64, 0x200000
	s_addc_u32 s49, s65, 0
	s_mov_b32 m0, s90
	v_lshl_add_u64 v[228:229], s[48:49], 0, v[130:131]
	ds_read_b128 v[180:183], v158 offset:32768
	ds_read_b128 v[184:187], v158 offset:33792
	ds_read_b128 v[188:191], v158 offset:34816
	ds_read_b128 v[192:195], v158 offset:35840
	ds_read_b128 v[196:199], v158 offset:36864
	ds_read_b128 v[208:211], v158 offset:37888
	ds_read_b128 v[212:215], v158 offset:38912
	ds_read_b128 v[216:219], v158 offset:39936
	global_load_lds_dwordx4 v[228:229], off
	v_lshl_add_u64 v[228:229], s[48:49], 0, v[128:129]
	s_mov_b32 m0, s91
	s_nop 0
	global_load_lds_dwordx4 v[228:229], off
	s_waitcnt vmcnt(8)
	s_waitcnt lgkmcnt(0)
	s_barrier
	s_setprio 1
	s_waitcnt lgkmcnt(0)
	v_mfma_f32_16x16x32_bf16 v[124:127], v[136:139], v[180:183], v[124:127]
	v_mfma_f32_16x16x32_bf16 v[120:123], v[154:157], v[180:183], v[120:123]
	v_mfma_f32_16x16x32_bf16 v[108:111], v[136:139], v[188:191], v[108:111]
	v_mfma_f32_16x16x32_bf16 v[104:107], v[154:157], v[188:191], v[104:107]
	v_mfma_f32_16x16x32_bf16 v[92:95], v[136:139], v[196:199], v[92:95]
	v_mfma_f32_16x16x32_bf16 v[88:91], v[154:157], v[196:199], v[88:91]
	v_mfma_f32_16x16x32_bf16 v[76:79], v[136:139], v[212:215], v[76:79]
	v_mfma_f32_16x16x32_bf16 v[72:75], v[154:157], v[212:215], v[72:75]
	v_mfma_f32_16x16x32_bf16 v[124:127], v[146:149], v[184:187], v[124:127]
	v_mfma_f32_16x16x32_bf16 v[120:123], v[160:163], v[184:187], v[120:123]
	v_mfma_f32_16x16x32_bf16 v[108:111], v[146:149], v[192:195], v[108:111]
	v_mfma_f32_16x16x32_bf16 v[104:107], v[160:163], v[192:195], v[104:107]
	v_mfma_f32_16x16x32_bf16 v[92:95], v[146:149], v[208:211], v[92:95]
	v_mfma_f32_16x16x32_bf16 v[88:91], v[160:163], v[208:211], v[88:91]
	v_mfma_f32_16x16x32_bf16 v[76:79], v[146:149], v[216:219], v[76:79]
	v_mfma_f32_16x16x32_bf16 v[72:75], v[160:163], v[216:219], v[72:75]
	s_setprio 0
	s_setprio 1
	v_mfma_f32_16x16x32_bf16 v[116:119], v[164:167], v[180:183], v[116:119]
	v_mfma_f32_16x16x32_bf16 v[112:115], v[172:175], v[180:183], v[112:115]
	v_mfma_f32_16x16x32_bf16 v[100:103], v[164:167], v[188:191], v[100:103]
	v_mfma_f32_16x16x32_bf16 v[96:99], v[172:175], v[188:191], v[96:99]
	v_mfma_f32_16x16x32_bf16 v[84:87], v[164:167], v[196:199], v[84:87]
	v_mfma_f32_16x16x32_bf16 v[80:83], v[172:175], v[196:199], v[80:83]
	v_mfma_f32_16x16x32_bf16 v[68:71], v[164:167], v[212:215], v[68:71]
	v_mfma_f32_16x16x32_bf16 v[64:67], v[172:175], v[212:215], v[64:67]
	v_mfma_f32_16x16x32_bf16 v[116:119], v[168:171], v[184:187], v[116:119]
	v_mfma_f32_16x16x32_bf16 v[112:115], v[176:179], v[184:187], v[112:115]
	v_mfma_f32_16x16x32_bf16 v[100:103], v[168:171], v[192:195], v[100:103]
	v_mfma_f32_16x16x32_bf16 v[96:99], v[176:179], v[192:195], v[96:99]
	v_mfma_f32_16x16x32_bf16 v[84:87], v[168:171], v[208:211], v[84:87]
	v_mfma_f32_16x16x32_bf16 v[80:83], v[176:179], v[208:211], v[80:83]
	v_mfma_f32_16x16x32_bf16 v[68:71], v[168:171], v[216:219], v[68:71]
	v_mfma_f32_16x16x32_bf16 v[64:67], v[176:179], v[216:219], v[64:67]
	s_setprio 0
	s_barrier
; #define PG8_STAGE(bufoff, gbase, voff) do { _Pragma("unroll") for (int _i = 0; _i < 2; ++_i) \
;         __builtin_amdgcn_global_load_lds((const unsigned*)((const char*)(gbase) + (voff)[_i]), (PG8_LAS unsigned*)(lds + (bufoff) + ldsw + _i * 8192), 16, 0, 0); } while (0)
; #define PG8_LDA(dst, b, h) do { _Pragma("unroll") for (int m = 0; m < 4; ++m) _Pragma("unroll") for (int k = 0; k < 2; ++k) dst[m][k] = *(const PG8_LAS bf16x8*)(lds + PG8_SA(b, h) + aoff + m * 2048 + k * 1024); } while (0)
; #define PG8_MMA(ai, bj, At, Bt) do { __builtin_amdgcn_s_setprio(1); _Pragma("unroll") for (int m = 0; m < 4; ++m) _Pragma("unroll") for (int n = 0; n < 2; ++n) _Pragma("unroll") for (int k = 0; k < 2; ++k) \
;         acc[ai][bj][m][n] = __builtin_amdgcn_mfma_f32_16x16x32_bf16(Bt[n][k], At[m][k], acc[ai][bj][m][n], 0, 0, 0); __builtin_amdgcn_s_setprio(0); } while (0)
; #define PG8_WAIT_V(n) asm volatile("s_waitcnt vmcnt(" #n ")" ::: "memory")
; #define PG8_WAIT_L(n) asm volatile("s_waitcnt lgkmcnt(" #n ")" ::: "memory")
; #define PG8_BAR __builtin_amdgcn_s_barrier()
; #define PG8_SCHED __builtin_amdgcn_sched_barrier(0)
; template <class Epi, class Sched, bool ALIGN_EPI = false, bool SP2 = false>
; __device__ __forceinline__ void gemm_phase(PG8_LAS unsigned char* lds, const Gemm g, const Sched& S, const Epi& E) {
;     ...
;         for (int t = 0; t < nt; t += 2) {
;     ...
;             PG8_LDA(At, 1, 1); PG8_STAGE(PG8_SB(1, 0), b3, voffB); PG8_STAGE(PG8_SB(1, 1), b3 + hstep, voffB); PG8_STAGE(PG8_SA(1, 0), a3, voffA);
;             PG8_WAIT_V(8); PG8_WAIT_L(0); PG8_BAR; PG8_MMA(1, 0, At, B0); PG8_MMA(1, 1, At, B1); PG8_BAR; PG8_SCHED;
	s_add_i32 s43, s43, s72
	v_lshl_add_u64 v[220:221], v[220:221], 0, s[84:85]
	s_mov_b32 m0, s43
	ds_read_b128 v[180:183], v158 offset:49152
	ds_read_b128 v[184:187], v158 offset:50176
	ds_read_b128 v[188:191], v158 offset:51200
	ds_read_b128 v[192:195], v158 offset:52224
	ds_read_b128 v[196:199], v158 offset:53248
	ds_read_b128 v[208:211], v158 offset:54272
	ds_read_b128 v[212:215], v158 offset:55296
	ds_read_b128 v[216:219], v158 offset:56320
	global_load_lds_dwordx4 v[220:221], off
	s_add_i32 m0, s43, 0x2000
	s_add_u32 s48, s62, 0x200080
	v_lshl_add_u64 v[220:221], v[222:223], 0, s[84:85]
	s_addc_u32 s49, s63, 0
	s_add_i32 s43, s61, s72
	global_load_lds_dwordx4 v[220:221], off
	v_lshl_add_u64 v[220:221], s[48:49], 0, v[130:131]
	s_mov_b32 m0, s43
	s_nop 0
	global_load_lds_dwordx4 v[220:221], off
	v_lshl_add_u64 v[220:221], s[48:49], 0, v[128:129]
	s_add_i32 m0, s43, 0x2000
	s_nop 0
	global_load_lds_dwordx4 v[220:221], off
	s_waitcnt vmcnt(4)
	s_waitcnt lgkmcnt(0)
	s_barrier
	s_setprio 1
	s_waitcnt lgkmcnt(0)
	v_mfma_f32_16x16x32_bf16 v[60:63], v[136:139], v[180:183], v[60:63]
	v_mfma_f32_16x16x32_bf16 v[56:59], v[154:157], v[180:183], v[56:59]
	v_mfma_f32_16x16x32_bf16 v[44:47], v[136:139], v[188:191], v[44:47]
	v_mfma_f32_16x16x32_bf16 v[40:43], v[154:157], v[188:191], v[40:43]
	v_mfma_f32_16x16x32_bf16 v[28:31], v[136:139], v[196:199], v[28:31]
	v_mfma_f32_16x16x32_bf16 v[24:27], v[154:157], v[196:199], v[24:27]
	v_mfma_f32_16x16x32_bf16 v[12:15], v[136:139], v[212:215], v[12:15]
	v_mfma_f32_16x16x32_bf16 v[8:11], v[154:157], v[212:215], v[8:11]
	v_mfma_f32_16x16x32_bf16 v[60:63], v[146:149], v[184:187], v[60:63]
	v_mfma_f32_16x16x32_bf16 v[56:59], v[160:163], v[184:187], v[56:59]
	v_mfma_f32_16x16x32_bf16 v[44:47], v[146:149], v[192:195], v[44:47]
	v_mfma_f32_16x16x32_bf16 v[40:43], v[160:163], v[192:195], v[40:43]
	v_mfma_f32_16x16x32_bf16 v[28:31], v[146:149], v[208:211], v[28:31]
	v_mfma_f32_16x16x32_bf16 v[24:27], v[160:163], v[208:211], v[24:27]
	v_mfma_f32_16x16x32_bf16 v[12:15], v[146:149], v[216:219], v[12:15]
	v_mfma_f32_16x16x32_bf16 v[8:11], v[160:163], v[216:219], v[8:11]
	s_setprio 0
	s_setprio 1
	v_mfma_f32_16x16x32_bf16 v[52:55], v[164:167], v[180:183], v[52:55]
	v_mfma_f32_16x16x32_bf16 v[48:51], v[172:175], v[180:183], v[48:51]
	v_mfma_f32_16x16x32_bf16 v[36:39], v[164:167], v[188:191], v[36:39]
	v_mfma_f32_16x16x32_bf16 v[32:35], v[172:175], v[188:191], v[32:35]
	v_mfma_f32_16x16x32_bf16 v[20:23], v[164:167], v[196:199], v[20:23]
	v_mfma_f32_16x16x32_bf16 v[16:19], v[172:175], v[196:199], v[16:19]
	v_mfma_f32_16x16x32_bf16 v[4:7], v[164:167], v[212:215], v[4:7]
	v_mfma_f32_16x16x32_bf16 v[0:3], v[172:175], v[212:215], v[0:3]
	v_mfma_f32_16x16x32_bf16 v[52:55], v[168:171], v[184:187], v[52:55]
	v_mfma_f32_16x16x32_bf16 v[48:51], v[176:179], v[184:187], v[48:51]
	v_mfma_f32_16x16x32_bf16 v[36:39], v[168:171], v[192:195], v[36:39]
	v_mfma_f32_16x16x32_bf16 v[32:35], v[176:179], v[192:195], v[32:35]
	v_mfma_f32_16x16x32_bf16 v[20:23], v[168:171], v[208:211], v[20:23]
	v_mfma_f32_16x16x32_bf16 v[16:19], v[176:179], v[208:211], v[16:19]
	v_mfma_f32_16x16x32_bf16 v[4:7], v[168:171], v[216:219], v[4:7]
	v_mfma_f32_16x16x32_bf16 v[0:3], v[176:179], v[216:219], v[0:3]
	s_setprio 0
	s_barrier
	s_add_i32 s96, s96, 2
	s_add_u32 s56, s56, 0x100
	s_addc_u32 s95, s95, 0
	s_cmpk_gt_u32 s96, 0x7d
	s_mov_b64 s[48:49], s[54:55]
	s_cbranch_scc0 .LBB0_1146
	s_and_b64 vcc, exec, s[16:17]
	s_cbranch_vccz .LBB0_1149
	s_barrier
